# P8 sample-row split-K re-cut: 22 slices of K=256 on 176 workgroups (was 11 x K512 on 88); P9 sums 22 partials
# baseline (speedup 1.0000x reference)
; #define PG8_WAIT_V(n) asm volatile("s_waitcnt vmcnt(" #n ")" ::: "memory")
; #define PG8_BAR __builtin_amdgcn_s_barrier()
;     __device__ bool next(int i, Unit& u) const { const long L = (long)i * G + c; if (L >= (long)nN * nks) return false;
;         u.pm = pm; u.pn = (int)(L % nN); u.ks = (int)(L / nN); u.koffA = u.ks * kchunk; u.koffB = u.koffA; return true; }
; template <class Epi, class Sched>
; __device__ __forceinline__ void gemm_phase(LAS unsigned char* lds, const Gemm g, const Sched& S, const Epi& E) {
;     const int tid = threadIdx.x, wid = __builtin_amdgcn_readfirstlane(tid >> 6), lane = tid & 63, wr = wid >> 2, wc = wid & 3, fr = lane & 15, fq = lane >> 4;
;     const int K = g.K, nt = K / BK;
;     unsigned voffA[2], voffB[2];
; #pragma unroll
;     for (int i = 0; i < 2; ++i) { int R, C; stage_rc(tid * 16 + i * 8192, R, C); const int Rb = Epi::PERM ? ((R & ~31) + perm32(R & 31)) : R;
;         voffA[i] = (unsigned)(R * g.lda + C) * 2u; voffB[i] = (unsigned)(Rb * g.ldb + C) * 2u; }
;     const size_t kstep = (size_t)(BK * 2);
;     const size_t hstepA = (size_t)HALF * g.lda * 2, hstepB = (size_t)HALF * g.ldb * 2;
;     const size_t tstepA = 2 * hstepA, tstepB = 2 * hstepB;
;     const unsigned ldsw = (unsigned)wid * 1024u;
;     const int aoff = lds_byte(wr * 64 + fr, fq * 8), boff = lds_byte(wc * 32 + fr, fq * 8);
;     ...
;     Unit cur, nxt; int ui = 0;
;     if (!S.next(0, cur)) return;
;     f32x4 acc[2][2][4][2];
; #pragma unroll
;     for (int a = 0; a < 2; ++a)
; #pragma unroll
;         for (int b = 0; b < 2; ++b)
; #pragma unroll
;             for (int m = 0; m < 4; ++m)
; #pragma unroll
;                 for (int n = 0; n < 2; ++n) acc[a][b][m][n] = (f32x4){0.f, 0.f, 0.f, 0.f};
;     bf16x8 At[4][2], B0[2][2], B1[2][2];
;     const char* cA = (const char*)g.A + (size_t)cur.pm * tstepA + (size_t)cur.koffA * 2; const char* cB = (const char*)g.Bt + (size_t)cur.pn * tstepB + (size_t)cur.koffB * 2;
;     PG8_STAGE(PG8_SB(0, 0), cB, voffB); PG8_STAGE(PG8_SA(0, 0), cA, voffA); PG8_STAGE(PG8_SB(0, 1), cB + hstepB, voffB); PG8_STAGE(PG8_SA(0, 1), cA + hstepA, voffA);
;     if (wr == 1) PG8_BAR;
;     PG8_WAIT_V(4); PG8_BAR;
;     PG8_STAGE(PG8_SB(1, 0), cB + kstep, voffB); PG8_STAGE(PG8_SA(1, 0), cA + kstep, voffA); PG8_STAGE(PG8_SB(1, 1), cB + hstepB + kstep, voffB);
;     PG8_WAIT_V(6); PG8_BAR;
.LBB0_1350:
	s_cmpk_gt_i32 s2, 0xaf
	v_readfirstlane_b32 s14, v196
	s_cbranch_scc1 .LBB0_1364
	s_ashr_i32 s22, s2, 31
	s_lshr_b32 s4, s22, 29
	s_add_i32 s4, s2, s4
	s_ashr_i32 s8, s4, 3
	s_and_b32 s4, s4, -8
	s_sub_i32 s9, s2, s4
	s_lshl_b32 s4, s8, 8
	s_lshr_b32 s1, s14, 6
	s_ashr_i32 s5, s4, 31
	s_lshr_b32 s0, s14, 8
	s_lshl_b32 s15, s1, 10
	s_lshl_b64 s[4:5], s[4:5], 1
	s_add_u32 s23, s90, 0xd700000
	s_mul_i32 s6, s9, 0x2c0000
	s_addc_u32 s26, s91, 0
	s_ashr_i32 s7, s6, 31
	v_readlane_b32 s10, v234, 7
	v_readlane_b32 s11, v234, 8
	s_add_u32 s6, s10, s6
	s_addc_u32 s7, s11, s7
	v_mul_u32_u24_e32 v8, 0x1600, v188
	v_lshrrev_b32_e32 v0, 1, v186
	v_mul_u32_u24_e32 v9, 0x1600, v187
	s_add_u32 s24, s6, s4
	v_or_b32_e32 v1, v8, v0
	v_or_b32_e32 v0, v0, v9
	s_addc_u32 s25, s7, s5
	s_add_i32 s27, s15, 0
	v_lshlrev_b32_e32 v66, 1, v0
	s_add_i32 m0, s27, 0x10000
	v_lshlrev_b32_e32 v64, 1, v1
	global_load_lds_dwordx4 v66, s[24:25]
	s_add_i32 m0, s27, 0x12000
	s_add_u32 s20, s23, s4
	global_load_lds_dwordx4 v64, s[24:25]
	s_addc_u32 s21, s26, s5
	s_mov_b32 m0, s27
	s_add_i32 s29, s27, 0x2000
	global_load_lds_dwordx4 v66, s[20:21]
	s_mov_b32 m0, s29
	s_add_u32 s4, s24, 0x160000
	global_load_lds_dwordx4 v64, s[20:21]
	s_addc_u32 s5, s25, 0
	s_add_i32 m0, s27, 0x14000
	v_mov_b32_e32 v67, 0
	global_load_lds_dwordx4 v66, s[4:5]
	s_add_i32 m0, s27, 0x16000
	v_mov_b32_e32 v65, v67
	global_load_lds_dwordx4 v64, s[4:5]
	s_add_u32 s4, s20, 0x160000
	s_addc_u32 s5, s21, 0
	s_add_i32 s30, s27, 0x4000
	s_mov_b32 m0, s30
	s_add_i32 s31, s27, 0x6000
	global_load_lds_dwordx4 v66, s[4:5]
	s_mov_b32 m0, s31
	s_mov_b32 s33, 0
	global_load_lds_dwordx4 v64, s[4:5]
	v_lshl_add_u64 v[6:7], s[24:25], 0, v[66:67]
	v_lshl_add_u64 v[4:5], s[24:25], 0, v[64:65]
	v_lshl_add_u64 v[2:3], s[20:21], 0, v[66:67]
	s_cmp_lg_u32 s0, 1
	v_lshl_add_u64 v[0:1], s[20:21], 0, v[64:65]
	s_cbranch_scc1 .LBB0_1353
	s_barrier
.LBB0_1353:
	s_mov_b64 s[10:11], 0x80
	s_lshl_b32 s1, s1, 5
	s_add_i32 m0, s27, 0x18000
	v_lshl_add_u64 v[6:7], v[6:7], 0, s[10:11]
	s_lshl_b32 s6, s0, 13
	s_and_b32 s1, s1, 0x60
	s_waitcnt vmcnt(4)
	s_barrier
	global_load_lds_dwordx4 v[6:7], off
	v_lshl_add_u64 v[4:5], v[4:5], 0, s[10:11]
	s_add_i32 m0, s27, 0x1a000
	s_add_i32 s34, s27, 0x8000
	s_add_i32 s35, s27, 0xa000
	global_load_lds_dwordx4 v[4:5], off
	v_lshl_add_u64 v[2:3], v[2:3], 0, s[10:11]
	s_mov_b32 m0, s34
	s_add_u32 s4, s24, 0x160080
	global_load_lds_dwordx4 v[2:3], off
	v_lshl_add_u64 v[0:1], v[0:1], 0, s[10:11]
	s_mov_b32 m0, s35
	s_addc_u32 s5, s25, 0
	global_load_lds_dwordx4 v[0:1], off
	s_add_i32 m0, s27, 0x1c000
	v_lshl_add_u64 v[0:1], s[4:5], 0, v[66:67]
	global_load_lds_dwordx4 v[0:1], off
	v_lshl_add_u64 v[0:1], s[4:5], 0, v[64:65]
	s_add_i32 m0, s27, 0x1e000
	v_lshlrev_b32_e32 v2, 2, v183
	global_load_lds_dwordx4 v[0:1], off
	v_lshl_or_b32 v0, s0, 6, v183
	v_lshl_or_b32 v1, v183, 6, v184
	v_and_b32_e32 v2, 32, v2
	v_bitop3_b32 v4, v1, s6, v2 bitop3:0xde
	v_mov_b32_e32 v1, v67
	v_or_b32_e32 v2, 16, v0
	v_mov_b32_e32 v3, v67
	v_lshlrev_b64 v[68:69], 13, v[0:1]
	v_lshlrev_b64 v[70:71], 13, v[2:3]
	v_or_b32_e32 v2, 32, v0
	v_or_b32_e32 v0, 48, v0
	s_waitcnt vmcnt(6)
	v_lshlrev_b64 v[74:75], 13, v[0:1]
	v_add_u16_e32 v0, v180, v181
	v_lshl_or_b32 v84, s1, 7, v185
	v_lshrrev_b16_e32 v0, 1, v0
	s_add_i32 s37, 0, 0x10000
	s_add_i32 s38, 0, 0x14000
	v_lshlrev_b64 v[72:73], 13, v[2:3]
	s_ashr_i32 s36, s3, 31
	v_lshl_or_b32 v85, v182, 2, s1
	v_add_lshl_u32 v76, v9, v0, 1
	v_mov_b32_e32 v77, v67
	v_add_lshl_u32 v78, v8, v0, 1
	v_mov_b32_e32 v79, v67
	v_mov_b64_e32 v[80:81], 0xb0
	v_mov_b64_e32 v[82:83], 0xaf
	v_add_u32_e32 v86, s37, v84
	v_add_u32_e32 v87, 0, v4
	v_add_u32_e32 v88, s38, v84
	s_add_i32 s39, s27, 0xc000
	s_add_i32 s40, s27, 0xe000
	s_barrier
.LBB0_1354:
	s_add_i32 s33, s33, 1
	s_mul_i32 s0, s33, s36
	s_mul_hi_u32 s1, s33, s3
	s_add_i32 s1, s1, s0
	s_mul_i32 s0, s33, s3
	s_add_u32 s4, s0, s2
	s_addc_u32 s5, s1, s22
	v_cmp_gt_i64_e64 s[0:1], s[4:5], v[82:83]
	v_cmp_lt_i64_e64 s[6:7], s[4:5], v[80:81]
	s_and_b64 vcc, exec, s[0:1]
	s_cbranch_vccnz .LBB0_1356
	s_ashr_i32 s12, s5, 31
	s_lshr_b32 s12, s12, 29
	s_add_u32 s12, s4, s12
	s_addc_u32 s13, s5, 0
	s_lshr_b64 s[12:13], s[12:13], 3
	s_lshl_b32 s5, s12, 3
	s_sub_i32 s13, s4, s5
	s_lshl_b32 s16, s12, 8

; #define PG8_STAGE(bufoff, gbase, voff) do { _Pragma("unroll") for (int _i = 0; _i < 2; ++_i) \
;         __builtin_amdgcn_global_load_lds((const unsigned*)((const char*)(gbase) + (voff)[_i]), (LAS unsigned*)(lds + (bufoff) + ldsw + _i * 8192), 16, 0, 0); } while (0)
; #define PG8_LDA(dst, b, h) do { _Pragma("unroll") for (int m = 0; m < 4; ++m) _Pragma("unroll") for (int k = 0; k < 2; ++k) dst[m][k] = *(const LAS bf16x8*)(lds + PG8_SA(b, h) + aoff + m * 2048 + k * 1024); } while (0)
; #define PG8_WAIT_V(n) asm volatile("s_waitcnt vmcnt(" #n ")" ::: "memory")
; #define PG8_WAIT_L(n) asm volatile("s_waitcnt lgkmcnt(" #n ")" ::: "memory")
; template <class Epi, class Sched>
; __device__ __forceinline__ void gemm_phase(LAS unsigned char* lds, const Gemm g, const Sched& S, const Epi& E) {
;     ...
;         for (int t = 0; t < nt; t += 2) {
;             const bool last = (t == nt - 2);
;             const char* a1 = cA + (size_t)(t + 1) * kstep;
;             const char* a2 = last ? nA : cA + (size_t)(t + 2) * kstep; const char* b2 = last ? nB : cB + (size_t)(t + 2) * kstep;
;             const char* a3 = a2 + kstep; const char* b3 = b2 + kstep;
;             PG8_LDB(B0, 0, 0); PG8_SCHED; PG8_LDA(At, 0, 0); PG8_STAGE(PG8_SA(1, 1), a1 + hstepA, voffA);
;             PG8_WAIT_L(8); PG8_BAR; PG8_WAIT_L(0); PG8_MMA(0, 0, At, B0); PG8_BAR; PG8_SCHED;
;             PG8_LDB(B1, 0, 1); PG8_STAGE(PG8_SB(0, 0), b2, voffB);
;             PG8_BAR; PG8_WAIT_L(0); PG8_MMA(0, 1, At, B1); PG8_BAR;
;             PG8_LDA(At, 0, 1); PG8_STAGE(PG8_SA(0, 0), a2, voffA);
;             PG8_BAR; PG8_WAIT_L(0); PG8_MMA(1, 0, At, B0); PG8_BAR; PG8_SCHED;
;             PG8_STAGE(PG8_SB(0, 1), b2 + hstepB, voffB);
;             PG8_WAIT_V(6); PG8_BAR; PG8_MMA(1, 1, At, B1); PG8_BAR;
;             PG8_LDB(B0, 1, 0); PG8_SCHED; PG8_LDA(At, 1, 0); PG8_STAGE(PG8_SA(0, 1), a2 + hstepA, voffA);
;             PG8_WAIT_L(8); PG8_BAR; PG8_WAIT_L(0); PG8_MMA(0, 0, At, B0); PG8_BAR; PG8_SCHED;
;             PG8_LDB(B1, 1, 1); PG8_STAGE(PG8_SB(1, 0), b3, voffB);
;             PG8_BAR; PG8_WAIT_L(0); PG8_MMA(0, 1, At, B1); PG8_BAR;
;             PG8_LDA(At, 1, 1); PG8_STAGE(PG8_SA(1, 0), a3, voffA);
;             PG8_BAR; PG8_WAIT_L(0); PG8_MMA(1, 0, At, B0); PG8_BAR; PG8_SCHED;
;             PG8_STAGE(PG8_SB(1, 1), b3 + hstepB, voffB);
;             PG8_WAIT_V(6); PG8_BAR; PG8_MMA(1, 1, At, B1); PG8_BAR;
.LBB0_1359:
	ds_read_b128 v[90:93], v86
	ds_read_b128 v[94:97], v86 offset:1024
	ds_read_b128 v[98:101], v86 offset:2048
	ds_read_b128 v[102:105], v86 offset:3072
	s_add_u32 s4, s20, 0xffea0080
	s_addc_u32 s5, s21, -1
	s_cmp_eq_u32 s42, 0
	s_cselect_b32 s5, s7, s5
	s_cselect_b32 s4, s6, s4
	s_cselect_b32 s25, s19, s41
	s_cselect_b32 s24, s18, s17
	s_mov_b32 m0, s39
	v_lshl_add_u64 v[138:139], s[20:21], 0, v[76:77]
	ds_read_b128 v[106:109], v87
	ds_read_b128 v[110:113], v87 offset:1024
	ds_read_b128 v[114:117], v87 offset:2048
	ds_read_b128 v[118:121], v87 offset:3072
	ds_read_b128 v[122:125], v87 offset:4096
	ds_read_b128 v[126:129], v87 offset:5120
	ds_read_b128 v[130:133], v87 offset:6144
	ds_read_b128 v[134:137], v87 offset:7168
	global_load_lds_dwordx4 v[138:139], off
	v_lshl_add_u64 v[138:139], s[20:21], 0, v[78:79]
	s_mov_b32 m0, s40
	s_nop 0
	global_load_lds_dwordx4 v[138:139], off
	s_waitcnt lgkmcnt(8)
	s_barrier
	s_waitcnt lgkmcnt(0)
	s_setprio 1
	s_waitcnt lgkmcnt(0)
	v_mfma_f32_16x16x32_bf16 v[60:63], v[90:93], v[106:109], v[60:63]
	v_mfma_f32_16x16x32_bf16 v[56:59], v[98:101], v[106:109], v[56:59]
	v_mfma_f32_16x16x32_bf16 v[52:55], v[90:93], v[114:117], v[52:55]
	v_mfma_f32_16x16x32_bf16 v[48:51], v[98:101], v[114:117], v[48:51]
	v_mfma_f32_16x16x32_bf16 v[44:47], v[90:93], v[122:125], v[44:47]
	v_mfma_f32_16x16x32_bf16 v[36:39], v[98:101], v[122:125], v[36:39]
	v_mfma_f32_16x16x32_bf16 v[28:31], v[90:93], v[130:133], v[28:31]
	v_mfma_f32_16x16x32_bf16 v[20:23], v[98:101], v[130:133], v[20:23]
	v_mfma_f32_16x16x32_bf16 v[60:63], v[94:97], v[110:113], v[60:63]
	v_mfma_f32_16x16x32_bf16 v[56:59], v[102:105], v[110:113], v[56:59]
	v_mfma_f32_16x16x32_bf16 v[52:55], v[94:97], v[118:121], v[52:55]
	v_mfma_f32_16x16x32_bf16 v[48:51], v[102:105], v[118:121], v[48:51]
	v_mfma_f32_16x16x32_bf16 v[44:47], v[94:97], v[126:129], v[44:47]
	v_mfma_f32_16x16x32_bf16 v[36:39], v[102:105], v[126:129], v[36:39]
	v_mfma_f32_16x16x32_bf16 v[28:31], v[94:97], v[134:137], v[28:31]
	v_mfma_f32_16x16x32_bf16 v[20:23], v[102:105], v[134:137], v[20:23]
	s_setprio 0
	s_barrier
	s_add_i32 s43, s37, s15
	v_lshl_add_u64 v[138:139], s[24:25], 0, v[66:67]
	s_mov_b32 m0, s43
	ds_read_b128 v[90:93], v88
	ds_read_b128 v[94:97], v88 offset:1024
	ds_read_b128 v[98:101], v88 offset:2048
	ds_read_b128 v[102:105], v88 offset:3072
	global_load_lds_dwordx4 v[138:139], off
	v_lshl_add_u64 v[140:141], s[24:25], 0, v[64:65]
	s_add_i32 m0, s43, 0x2000
	s_nop 0
	global_load_lds_dwordx4 v[140:141], off
	s_barrier
	s_waitcnt lgkmcnt(0)
	s_setprio 1
	s_waitcnt lgkmcnt(0)
	v_mfma_f32_16x16x32_bf16 v[40:43], v[90:93], v[106:109], v[40:43]
	v_mfma_f32_16x16x32_bf16 v[32:35], v[98:101], v[106:109], v[32:35]
	v_mfma_f32_16x16x32_bf16 v[24:27], v[90:93], v[114:117], v[24:27]
	v_mfma_f32_16x16x32_bf16 v[16:19], v[98:101], v[114:117], v[16:19]
	v_mfma_f32_16x16x32_bf16 v[12:15], v[90:93], v[122:125], v[12:15]
	v_mfma_f32_16x16x32_bf16 v[8:11], v[98:101], v[122:125], v[8:11]
	v_mfma_f32_16x16x32_bf16 v[4:7], v[90:93], v[130:133], v[4:7]
	v_mfma_f32_16x16x32_bf16 v[0:3], v[98:101], v[130:133], v[0:3]
	v_mfma_f32_16x16x32_bf16 v[40:43], v[94:97], v[110:113], v[40:43]
	v_mfma_f32_16x16x32_bf16 v[32:35], v[102:105], v[110:113], v[32:35]
	v_mfma_f32_16x16x32_bf16 v[24:27], v[94:97], v[118:121], v[24:27]
	v_mfma_f32_16x16x32_bf16 v[16:19], v[102:105], v[118:121], v[16:19]
	v_mfma_f32_16x16x32_bf16 v[12:15], v[94:97], v[126:129], v[12:15]
	v_mfma_f32_16x16x32_bf16 v[8:11], v[102:105], v[126:129], v[8:11]
	v_mfma_f32_16x16x32_bf16 v[4:7], v[94:97], v[134:137], v[4:7]
	v_mfma_f32_16x16x32_bf16 v[0:3], v[102:105], v[134:137], v[0:3]
	s_setprio 0
	s_mov_b32 m0, s27
	v_lshl_add_u64 v[142:143], s[4:5], 0, v[66:67]
	s_barrier
	global_load_lds_dwordx4 v[142:143], off
	v_lshl_add_u64 v[144:145], s[4:5], 0, v[64:65]
	s_mov_b32 m0, s29
	s_nop 0
	global_load_lds_dwordx4 v[144:145], off
	s_barrier
	s_waitcnt lgkmcnt(0)
	s_setprio 1
	s_setprio 0
	s_barrier
	s_add_u32 s44, s24, 0x160000
	s_addc_u32 s45, s25, 0
	s_add_i32 s43, s38, s15
	v_lshl_add_u64 v[90:91], s[44:45], 0, v[66:67]
	s_mov_b32 m0, s43
	s_nop 0
	global_load_lds_dwordx4 v[90:91], off
	v_lshl_add_u64 v[90:91], s[44:45], 0, v[64:65]
	s_add_i32 m0, s43, 0x2000
	s_nop 0
	global_load_lds_dwordx4 v[90:91], off
	s_waitcnt vmcnt(6)
	s_barrier
	s_setprio 1
	s_setprio 0
	s_add_i32 s43, 0, 0x18000
	v_add_u32_e32 v89, s43, v84
	s_barrier
	ds_read_b128 v[90:93], v89
	ds_read_b128 v[94:97], v89 offset:1024
	ds_read_b128 v[98:101], v89 offset:2048
	ds_read_b128 v[102:105], v89 offset:3072
	s_add_u32 s4, s4, 0x160000
	s_addc_u32 s5, s5, 0
	s_mov_b32 m0, s30
	v_lshl_add_u64 v[146:147], s[4:5], 0, v[66:67]
	ds_read_b128 v[106:109], v87 offset:32768
	ds_read_b128 v[110:113], v87 offset:33792
	ds_read_b128 v[114:117], v87 offset:34816
	ds_read_b128 v[118:121], v87 offset:35840
	ds_read_b128 v[122:125], v87 offset:36864
	ds_read_b128 v[126:129], v87 offset:37888
	ds_read_b128 v[130:133], v87 offset:38912
	ds_read_b128 v[134:137], v87 offset:39936
	global_load_lds_dwordx4 v[146:147], off
	v_lshl_add_u64 v[146:147], s[4:5], 0, v[64:65]
	s_mov_b32 m0, s31
	s_nop 0
	global_load_lds_dwordx4 v[146:147], off
	s_waitcnt lgkmcnt(8)
	s_barrier
; #define PG8_STAGE(bufoff, gbase, voff) do { _Pragma("unroll") for (int _i = 0; _i < 2; ++_i) \
;         __builtin_amdgcn_global_load_lds((const unsigned*)((const char*)(gbase) + (voff)[_i]), (LAS unsigned*)(lds + (bufoff) + ldsw + _i * 8192), 16, 0, 0); } while (0)
; #define PG8_LDA(dst, b, h) do { _Pragma("unroll") for (int m = 0; m < 4; ++m) _Pragma("unroll") for (int k = 0; k < 2; ++k) dst[m][k] = *(const LAS bf16x8*)(lds + PG8_SA(b, h) + aoff + m * 2048 + k * 1024); } while (0)
; #define PG8_MMA(ai, bj, At, Bt) do { __builtin_amdgcn_s_setprio(1); _Pragma("unroll") for (int m = 0; m < 4; ++m) _Pragma("unroll") for (int n = 0; n < 2; ++n) _Pragma("unroll") for (int k = 0; k < 2; ++k) \
;         acc[ai][bj][m][n] = __builtin_amdgcn_mfma_f32_16x16x32_bf16(Bt[n][k], At[m][k], acc[ai][bj][m][n], 0, 0, 0); __builtin_amdgcn_s_setprio(0); } while (0)
; #define PG8_WAIT_V(n) asm volatile("s_waitcnt vmcnt(" #n ")" ::: "memory")
; #define PG8_WAIT_L(n) asm volatile("s_waitcnt lgkmcnt(" #n ")" ::: "memory")
; #define PG8_BAR __builtin_amdgcn_s_barrier()
; #define PG8_SCHED __builtin_amdgcn_sched_barrier(0)
; template <class Epi, class Sched>
; __device__ __forceinline__ void gemm_phase(LAS unsigned char* lds, const Gemm g, const Sched& S, const Epi& E) {
;     ...
;             PG8_BAR; PG8_WAIT_L(0); PG8_MMA(0, 1, At, B1); PG8_BAR;
;             PG8_LDA(At, 1, 1); PG8_STAGE(PG8_SA(1, 0), a3, voffA);
;             PG8_BAR; PG8_WAIT_L(0); PG8_MMA(1, 0, At, B0); PG8_BAR; PG8_SCHED;
;             PG8_STAGE(PG8_SB(1, 1), b3 + hstepB, voffB);
;             PG8_WAIT_V(6); PG8_BAR; PG8_MMA(1, 1, At, B1); PG8_BAR;
;         }
;         if constexpr (!Epi::AFTER_DRAIN) E(acc, cur, wr, wc, fr, fq);
;         if (!has_next) break;
;     __device__ __forceinline__ void operator()(const f32x4 (&acc)[2][2][4][2], const Unit& u, int wr, int wc, int fr, int fq) const {
;         const int col0 = u.pn * 256 + wc * 32 + 4 * fq;
; #pragma unroll
;         for (int m = 0; m < 4; ++m) {
;             const int lrow = wr * 64 + m * 16 + fr;
;             float* p = buf + ((size_t)u.ks * MSA + lrow) * D + col0;
; #pragma unroll
;             for (int bj = 0; bj < 2; ++bj)
; #pragma unroll
;                 for (int n = 0; n < 2; ++n) *(f32x4*)(p + bj * 128 + n * 16) = acc[0][bj][m][n];
;         }
	s_waitcnt lgkmcnt(0)
	s_setprio 1
	s_waitcnt lgkmcnt(0)
	v_mfma_f32_16x16x32_bf16 v[60:63], v[90:93], v[106:109], v[60:63]
	v_mfma_f32_16x16x32_bf16 v[56:59], v[98:101], v[106:109], v[56:59]
	v_mfma_f32_16x16x32_bf16 v[52:55], v[90:93], v[114:117], v[52:55]
	v_mfma_f32_16x16x32_bf16 v[48:51], v[98:101], v[114:117], v[48:51]
	v_mfma_f32_16x16x32_bf16 v[44:47], v[90:93], v[122:125], v[44:47]
	v_mfma_f32_16x16x32_bf16 v[36:39], v[98:101], v[122:125], v[36:39]
	v_mfma_f32_16x16x32_bf16 v[28:31], v[90:93], v[130:133], v[28:31]
	v_mfma_f32_16x16x32_bf16 v[20:23], v[98:101], v[130:133], v[20:23]
	v_mfma_f32_16x16x32_bf16 v[60:63], v[94:97], v[110:113], v[60:63]
	v_mfma_f32_16x16x32_bf16 v[56:59], v[102:105], v[110:113], v[56:59]
	v_mfma_f32_16x16x32_bf16 v[52:55], v[94:97], v[118:121], v[52:55]
	v_mfma_f32_16x16x32_bf16 v[48:51], v[102:105], v[118:121], v[48:51]
	v_mfma_f32_16x16x32_bf16 v[44:47], v[94:97], v[126:129], v[44:47]
	v_mfma_f32_16x16x32_bf16 v[36:39], v[102:105], v[126:129], v[36:39]
	v_mfma_f32_16x16x32_bf16 v[28:31], v[94:97], v[134:137], v[28:31]
	v_mfma_f32_16x16x32_bf16 v[20:23], v[102:105], v[134:137], v[20:23]
	s_setprio 0
	s_barrier
	s_add_i32 s44, 0, 0x1c000
	s_add_i32 s4, s43, s15
	v_add_u32_e32 v89, s44, v84
	v_lshl_add_u64 v[138:139], v[138:139], 0, s[10:11]
	s_mov_b32 m0, s4
	ds_read_b128 v[90:93], v89
	ds_read_b128 v[94:97], v89 offset:1024
	ds_read_b128 v[98:101], v89 offset:2048
	ds_read_b128 v[102:105], v89 offset:3072
	global_load_lds_dwordx4 v[138:139], off
	v_lshl_add_u64 v[138:139], v[140:141], 0, s[10:11]
	s_add_i32 m0, s4, 0x2000
	s_nop 0
	global_load_lds_dwordx4 v[138:139], off
	s_barrier
	s_waitcnt lgkmcnt(0)
	s_setprio 1
	s_waitcnt lgkmcnt(0)
	v_mfma_f32_16x16x32_bf16 v[40:43], v[90:93], v[106:109], v[40:43]
	v_mfma_f32_16x16x32_bf16 v[32:35], v[98:101], v[106:109], v[32:35]
	v_mfma_f32_16x16x32_bf16 v[24:27], v[90:93], v[114:117], v[24:27]
	v_mfma_f32_16x16x32_bf16 v[16:19], v[98:101], v[114:117], v[16:19]
	v_mfma_f32_16x16x32_bf16 v[12:15], v[90:93], v[122:125], v[12:15]
	v_mfma_f32_16x16x32_bf16 v[8:11], v[98:101], v[122:125], v[8:11]
	v_mfma_f32_16x16x32_bf16 v[4:7], v[90:93], v[130:133], v[4:7]
	v_mfma_f32_16x16x32_bf16 v[0:3], v[98:101], v[130:133], v[0:3]
	v_mfma_f32_16x16x32_bf16 v[40:43], v[94:97], v[110:113], v[40:43]
	v_mfma_f32_16x16x32_bf16 v[32:35], v[102:105], v[110:113], v[32:35]
	v_mfma_f32_16x16x32_bf16 v[24:27], v[94:97], v[118:121], v[24:27]
	v_mfma_f32_16x16x32_bf16 v[16:19], v[102:105], v[118:121], v[16:19]
	v_mfma_f32_16x16x32_bf16 v[12:15], v[94:97], v[126:129], v[12:15]
	v_mfma_f32_16x16x32_bf16 v[8:11], v[102:105], v[126:129], v[8:11]
	v_mfma_f32_16x16x32_bf16 v[4:7], v[94:97], v[134:137], v[4:7]
	v_mfma_f32_16x16x32_bf16 v[0:3], v[102:105], v[134:137], v[0:3]
	s_setprio 0
	s_mov_b32 m0, s34
	v_lshl_add_u64 v[90:91], v[142:143], 0, s[10:11]
	s_barrier
	global_load_lds_dwordx4 v[90:91], off
	v_lshl_add_u64 v[90:91], v[144:145], 0, s[10:11]
	s_mov_b32 m0, s35
	s_nop 0
	global_load_lds_dwordx4 v[90:91], off
	s_barrier
	s_waitcnt lgkmcnt(0)
	s_setprio 1
	s_setprio 0
	s_barrier
	s_add_u32 s4, s24, 0x160080
	s_addc_u32 s5, s25, 0
	s_add_i32 s24, s44, s15
	v_lshl_add_u64 v[90:91], s[4:5], 0, v[66:67]
	s_mov_b32 m0, s24
	s_nop 0
	global_load_lds_dwordx4 v[90:91], off
	v_lshl_add_u64 v[90:91], s[4:5], 0, v[64:65]
	s_add_i32 m0, s24, 0x2000
	s_nop 0
	global_load_lds_dwordx4 v[90:91], off
	s_waitcnt vmcnt(6)
	s_barrier
	s_setprio 1
	s_setprio 0
	s_add_i32 s42, s42, 2
	s_add_u32 s20, s20, 0x100
	s_addc_u32 s21, s21, 0
	s_add_u32 s17, s17, 0x100
	s_addc_u32 s41, s41, 0
	s_cmp_gt_u32 s42, 1
	s_barrier
	s_cbranch_scc0 .LBB0_1359
	v_lshl_or_b32 v90, s9, 8, v85
	s_ashr_i32 s9, s8, 31
	s_lshl_b64 s[4:5], s[8:9], 20
	s_add_u32 s4, s46, s4
	v_ashrrev_i32_e32 v91, 31, v90
	s_addc_u32 s5, s47, s5
	v_lshl_add_u64 v[92:93], s[4:5], 0, v[68:69]
	v_lshlrev_b64 v[90:91], 2, v[90:91]
	v_lshl_add_u64 v[92:93], v[92:93], 0, v[90:91]
	global_store_dwordx4 v[92:93], v[60:63], off
	global_store_dwordx4 v[92:93], v[56:59], off offset:64
	global_store_dwordx4 v[92:93], v[40:43], off offset:512
	global_store_dwordx4 v[92:93], v[32:35], off offset:576
	s_and_b64 vcc, exec, s[0:1]
	s_mov_b32 s8, s12
	v_lshl_add_u64 v[32:33], s[4:5], 0, v[70:71]
	v_lshl_add_u64 v[32:33], v[32:33], 0, v[90:91]
	global_store_dwordx4 v[32:33], v[52:55], off
	global_store_dwordx4 v[32:33], v[48:51], off offset:64
	global_store_dwordx4 v[32:33], v[24:27], off offset:512
	global_store_dwordx4 v[32:33], v[16:19], off offset:576
	s_mov_b32 s9, s13
	s_mov_b64 s[24:25], s[18:19]
	v_lshl_add_u64 v[16:17], s[4:5], 0, v[72:73]
	v_lshl_add_u64 v[16:17], v[16:17], 0, v[90:91]
	global_store_dwordx4 v[16:17], v[44:47], off
	global_store_dwordx4 v[16:17], v[36:39], off offset:64
	global_store_dwordx4 v[16:17], v[12:15], off offset:512
	global_store_dwordx4 v[16:17], v[8:11], off offset:576
	s_mov_b64 s[20:21], s[6:7]
	s_nop 0
	v_lshl_add_u64 v[8:9], s[4:5], 0, v[74:75]
	v_lshl_add_u64 v[8:9], v[8:9], 0, v[90:91]
	global_store_dwordx4 v[8:9], v[28:31], off
	global_store_dwordx4 v[8:9], v[20:23], off offset:64
	global_store_dwordx4 v[8:9], v[4:7], off offset:512
	global_store_dwordx4 v[8:9], v[0:3], off offset:576
	s_cbranch_vccz .LBB0_1354
	s_waitcnt vmcnt(0)
	s_cmpk_gt_u32 s14, 0xff
	s_cbranch_scc1 .LBB0_1363
	s_barrier

; __global__ void __launch_bounds__(NTHR) hymba_fwd(Params P) {
;     ...
;         for (int row = (G == 256 ? MPR : 0) + gwave; row < MV; row += gwaves) {
;             float* p = out + (size_t)row * D; f32x4 v[8]; float s = 0.f;
; #pragma unroll
;             for (int i = 0; i < 8; ++i) v[i] = *(const f32x4*)(p + (i * 64 + lane) * 4);
;             if (row >= MPR) {
; #pragma unroll
;                 for (int i = 0; i < 8; ++i)
; #pragma unroll
;                     for (int ks = 0; ks < KS8; ++ks) v[i] = v[i] + *(const f32x4*)(Part8 + ((size_t)ks * MSA + (row - MPR)) * D + (i * 64 + lane) * 4);
;             }
; #pragma unroll
;             for (int i = 0; i < 8; ++i) s += (v[i][0] * v[i][0] + v[i][1] * v[i][1]) + (v[i][2] * v[i][2] + v[i][3] * v[i][3]);
;             s = wsum(s); const float rstd = rsqrtf(s * (1.0f / D) + RMS_EPS);
; #pragma unroll
;             for (int i = 0; i < 8; ++i) { const int c = (i * 64 + lane) * 4; *(f32x4*)(p + c) = v[i] * rstd * *(const f32x4*)(norm_final + c); }
.LBB0_1418:
	s_cmp_eq_u32 s95, 9
	s_cselect_b64 s[0:1], -1, 0
	s_or_b64 s[0:1], s[92:93], s[0:1]
	s_andn2_b64 vcc, exec, s[0:1]
	s_cbranch_vccnz .LBB0_1424
	s_cmpk_lg_i32 s3, 0x100
	s_cbranch_scc1 .Lp9_generic
	s_cmpk_gt_u32 s2, 0x7f
	s_cbranch_scc1 .LBB0_1424
	v_readfirstlane_b32 s0, v196
	v_and_b32_e32 v0, 63, v196
	v_readlane_b32 s4, v234, 0
	v_readlane_b32 s5, v234, 1
	s_lshr_b32 s0, s0, 6
	v_lshlrev_b32_e32 v0, 4, v0
	s_lshl_b32 s1, s0, 10
	v_add_u32_e32 v0, s1, v0
	s_sub_u32 s4, s4, 0xe8
	s_subb_u32 s5, s5, 0
	s_load_dwordx2 s[6:7], s[4:5], 0xc8
	s_addk_i32 s2, 0x2000
	s_lshl_b32 s9, s2, 13
	s_add_u32 s10, s88, s9
	s_addc_u32 s11, s89, 0
	s_add_i32 s9, s9, 0xfc000000
	s_add_u32 s12, s90, 0x5e00000
	s_addc_u32 s13, s91, 0
	s_add_u32 s12, s12, s9
	s_addc_u32 s13, s13, 0
	global_load_dwordx4 v[4:7], v0, s[10:11]
	global_load_dwordx4 v[8:11], v0, s[12:13]
	s_add_u32 s12, s12, 0x100000
	s_addc_u32 s13, s13, 0
	global_load_dwordx4 v[12:15], v0, s[12:13]
	s_add_u32 s12, s12, 0x100000
	s_addc_u32 s13, s13, 0
	global_load_dwordx4 v[16:19], v0, s[12:13]
	s_add_u32 s12, s12, 0x100000
	s_addc_u32 s13, s13, 0
	global_load_dwordx4 v[20:23], v0, s[12:13]
	s_add_u32 s12, s12, 0x100000
	s_addc_u32 s13, s13, 0
	global_load_dwordx4 v[24:27], v0, s[12:13]
	s_add_u32 s12, s12, 0x100000
	s_addc_u32 s13, s13, 0
	global_load_dwordx4 v[28:31], v0, s[12:13]
	s_add_u32 s12, s12, 0x100000
	s_addc_u32 s13, s13, 0
	global_load_dwordx4 v[32:35], v0, s[12:13]
	s_add_u32 s12, s12, 0x100000
	s_addc_u32 s13, s13, 0
	global_load_dwordx4 v[36:39], v0, s[12:13]
	s_add_u32 s12, s12, 0x100000
	s_addc_u32 s13, s13, 0
	global_load_dwordx4 v[40:43], v0, s[12:13]
	s_add_u32 s12, s12, 0x100000
	s_addc_u32 s13, s13, 0
	global_load_dwordx4 v[44:47], v0, s[12:13]
	s_add_u32 s12, s12, 0x100000
	s_addc_u32 s13, s13, 0
	global_load_dwordx4 v[48:51], v0, s[12:13]
	s_add_u32 s12, s12, 0x100000
	s_addc_u32 s13, s13, 0
	global_load_dwordx4 v[52:55], v0, s[12:13]
	s_add_u32 s12, s12, 0x100000
	s_addc_u32 s13, s13, 0
	global_load_dwordx4 v[56:59], v0, s[12:13]
	s_add_u32 s12, s12, 0x100000
	s_addc_u32 s13, s13, 0
	global_load_dwordx4 v[60:63], v0, s[12:13]
	s_add_u32 s12, s12, 0x100000
	s_addc_u32 s13, s13, 0
	global_load_dwordx4 v[64:67], v0, s[12:13]
	s_add_u32 s12, s12, 0x100000
	s_addc_u32 s13, s13, 0
	global_load_dwordx4 v[68:71], v0, s[12:13]
	s_add_u32 s12, s12, 0x100000
	s_addc_u32 s13, s13, 0
	global_load_dwordx4 v[72:75], v0, s[12:13]
	s_add_u32 s12, s12, 0x100000
	s_addc_u32 s13, s13, 0
	global_load_dwordx4 v[76:79], v0, s[12:13]
	s_add_u32 s12, s12, 0x100000
	s_addc_u32 s13, s13, 0
	global_load_dwordx4 v[80:83], v0, s[12:13]
	s_add_u32 s12, s12, 0x100000
	s_addc_u32 s13, s13, 0
	global_load_dwordx4 v[84:87], v0, s[12:13]
	s_add_u32 s12, s12, 0x100000
	s_addc_u32 s13, s13, 0
	global_load_dwordx4 v[88:91], v0, s[12:13]
	s_add_u32 s12, s12, 0x100000
	s_addc_u32 s13, s13, 0
	global_load_dwordx4 v[92:95], v0, s[12:13]
	s_waitcnt lgkmcnt(0)
	global_load_dwordx4 v[100:103], v0, s[6:7]
	s_waitcnt vmcnt(22)
	v_pk_add_f32 v[4:5], v[4:5], v[8:9]
	v_pk_add_f32 v[6:7], v[6:7], v[10:11]
	s_waitcnt vmcnt(21)
	v_pk_add_f32 v[4:5], v[4:5], v[12:13]
	v_pk_add_f32 v[6:7], v[6:7], v[14:15]
	s_waitcnt vmcnt(20)
	v_pk_add_f32 v[4:5], v[4:5], v[16:17]
	v_pk_add_f32 v[6:7], v[6:7], v[18:19]
	s_waitcnt vmcnt(19)
	v_pk_add_f32 v[4:5], v[4:5], v[20:21]
	v_pk_add_f32 v[6:7], v[6:7], v[22:23]
	s_waitcnt vmcnt(18)
	v_pk_add_f32 v[4:5], v[4:5], v[24:25]
	v_pk_add_f32 v[6:7], v[6:7], v[26:27]
	s_waitcnt vmcnt(17)
	v_pk_add_f32 v[4:5], v[4:5], v[28:29]
	v_pk_add_f32 v[6:7], v[6:7], v[30:31]
	s_waitcnt vmcnt(16)
	v_pk_add_f32 v[4:5], v[4:5], v[32:33]
	v_pk_add_f32 v[6:7], v[6:7], v[34:35]
	s_waitcnt vmcnt(15)
	v_pk_add_f32 v[4:5], v[4:5], v[36:37]
	v_pk_add_f32 v[6:7], v[6:7], v[38:39]
	s_waitcnt vmcnt(14)
	v_pk_add_f32 v[4:5], v[4:5], v[40:41]
	v_pk_add_f32 v[6:7], v[6:7], v[42:43]
	s_waitcnt vmcnt(13)
	v_pk_add_f32 v[4:5], v[4:5], v[44:45]
	v_pk_add_f32 v[6:7], v[6:7], v[46:47]
	s_waitcnt vmcnt(12)
	v_pk_add_f32 v[4:5], v[4:5], v[48:49]
	v_pk_add_f32 v[6:7], v[6:7], v[50:51]
	s_waitcnt vmcnt(11)
	v_pk_add_f32 v[4:5], v[4:5], v[52:53]
	v_pk_add_f32 v[6:7], v[6:7], v[54:55]
	s_waitcnt vmcnt(10)
	v_pk_add_f32 v[4:5], v[4:5], v[56:57]
	v_pk_add_f32 v[6:7], v[6:7], v[58:59]
	s_waitcnt vmcnt(9)
	v_pk_add_f32 v[4:5], v[4:5], v[60:61]
	v_pk_add_f32 v[6:7], v[6:7], v[62:63]
	s_waitcnt vmcnt(8)
	v_pk_add_f32 v[4:5], v[4:5], v[64:65]
	v_pk_add_f32 v[6:7], v[6:7], v[66:67]
	s_waitcnt vmcnt(7)
	v_pk_add_f32 v[4:5], v[4:5], v[68:69]
	v_pk_add_f32 v[6:7], v[6:7], v[70:71]
	s_waitcnt vmcnt(6)
	v_pk_add_f32 v[4:5], v[4:5], v[72:73]
	v_pk_add_f32 v[6:7], v[6:7], v[74:75]
	s_waitcnt vmcnt(5)
	v_pk_add_f32 v[4:5], v[4:5], v[76:77]
	v_pk_add_f32 v[6:7], v[6:7], v[78:79]
	s_waitcnt vmcnt(4)
	v_pk_add_f32 v[4:5], v[4:5], v[80:81]
	v_pk_add_f32 v[6:7], v[6:7], v[82:83]
	s_waitcnt vmcnt(3)
	v_pk_add_f32 v[4:5], v[4:5], v[84:85]
	v_pk_add_f32 v[6:7], v[6:7], v[86:87]
	s_waitcnt vmcnt(2)
	v_pk_add_f32 v[4:5], v[4:5], v[88:89]
	v_pk_add_f32 v[6:7], v[6:7], v[90:91]
	s_waitcnt vmcnt(1)
	v_pk_add_f32 v[4:5], v[4:5], v[92:93]
	v_pk_add_f32 v[6:7], v[6:7], v[94:95]
	v_pk_mul_f32 v[104:105], v[4:5], v[4:5]
	v_pk_fma_f32 v[104:105], v[6:7], v[6:7], v[104:105]
	s_lshl_b32 s18, s0, 2
	v_mov_b32_e32 v106, s18
	v_add_f32_e32 v104, v104, v105
	s_nop 1
	v_add_f32_dpp v104, v104, v104 quad_perm:[1,0,3,2] row_mask:0xf bank_mask:0xf bound_ctrl:1
	s_nop 1
	v_add_f32_dpp v104, v104, v104 quad_perm:[2,3,0,1] row_mask:0xf bank_mask:0xf bound_ctrl:1
	s_nop 1
	v_add_f32_dpp v104, v104, v104 row_half_mirror row_mask:0xf bank_mask:0xf bound_ctrl:1
	s_nop 1
	v_add_f32_dpp v104, v104, v104 row_mirror row_mask:0xf bank_mask:0xf bound_ctrl:1
	s_nop 1
	v_readlane_b32 s14, v104, 0
	v_readlane_b32 s15, v104, 16
	v_readlane_b32 s16, v104, 32
	v_readlane_b32 s17, v104, 48
	s_nop 1
	v_mov_b32_e32 v105, s14
	v_add_f32_e32 v105, s15, v105
	v_add_f32_e32 v105, s16, v105
	v_add_f32_e32 v105, s17, v105
	ds_write_b32 v106, v105
	v_mov_b32_e32 v106, 0
	s_waitcnt lgkmcnt(0)
	s_barrier
	ds_read_b128 v[108:111], v106
	ds_read_b128 v[112:115], v106 offset:16
	v_mov_b32_e32 v116, 0x3a000000
	v_mov_b32_e32 v117, 0x358637bd
	s_waitcnt lgkmcnt(0)
	v_add_f32_e32 v108, v108, v109
	v_add_f32_e32 v110, v110, v111
	v_add_f32_e32 v112, v112, v113
	v_add_f32_e32 v114, v114, v115
	v_add_f32_e32 v108, v108, v110
	v_add_f32_e32 v112, v112, v114
	v_add_f32_e32 v108, v108, v112
	v_fma_f32 v108, v108, v116, v117
	v_rsq_f32_e32 v108, v108
	s_waitcnt vmcnt(0)
	s_nop 0
	v_pk_mul_f32 v[4:5], v[4:5], v[108:109] op_sel_hi:[1,0]
	v_pk_mul_f32 v[6:7], v[6:7], v[108:109] op_sel_hi:[1,0]
	v_pk_mul_f32 v[4:5], v[4:5], v[100:101]
	v_pk_mul_f32 v[6:7], v[6:7], v[102:103]
	global_store_dwordx4 v0, v[4:7], s[10:11]
	s_branch .LBB0_1424
